# gdn_prep: l2-norm 16-lane reductions by DPP adds instead of ds_bpermute round trips (bitwise-identical sums)
# baseline (speedup 1.0000x reference)
; DI float bf_lo(unsigned u) { return __uint_as_float(u << 16); }
; DI float bf_hi(unsigned u) { return __uint_as_float(u & 0xffff0000u); }
; DI float sigmoidf_(float x) { return __builtin_amdgcn_rcpf(1.0f + __expf(-x)); }
; DI void phase_gdn_prep(const Params& P, int l) {
;     ...
;             for (int rr = 0; rr < 7; ++rr) {
;                 if (tgl == 0 && rr < 3) {
;                     if (s0 > 0) x[rr] = *(const u32x4*)(halo + ((size_t)(rb - 1) * 3 + rr) * 1536 + c);
;                     else x[rr] = (u32x4){0u, 0u, 0u, 0u};
;                 } else x[rr] = *(const u32x4*)(proj + (size_t)(t0 - 3 + rr) * PJ + 768 + c);
;             }
; #pragma unroll
;             for (int tk = 0; tk < 4; ++tk) {
;                 float y[8];
; #pragma unroll
;                 for (int e = 0; e < 8; ++e) y[e] = 0.f;
; #pragma unroll
;                 for (int i = 0; i < 4; ++i)
; #pragma unroll
;                     for (int jj = 0; jj < 4; ++jj) {
;                         y[2 * jj] += w[i][jj >> 1][(2 * jj) & 3] * bf_lo(x[tk + i][jj]);
;                         y[2 * jj + 1] += w[i][jj >> 1][(2 * jj + 1) & 3] * bf_hi(x[tk + i][jj]);
;                     }
;                 float ss = 0.f;
; #pragma unroll
;                 for (int e = 0; e < 8; ++e) { y[e] = y[e] * sigmoidf_(y[e]); ss += y[e] * y[e]; }
;                 if (which < 2) {
;                     ss += __shfl_xor(ss, 1); ss += __shfl_xor(ss, 2); ss += __shfl_xor(ss, 4); ss += __shfl_xor(ss, 8);
;                     float sc = rsqrtf(ss + 1e-6f);
;                     if (which == 0) sc *= 0.08838834764831845f;
; #pragma unroll
;                     for (int e = 0; e < 8; ++e) y[e] *= sc;
;                 }
.LBB0_41:
	s_or_b64 exec, exec, s[14:15]
	v_mov_b64_e32 v[32:33], s[90:91]
	v_mad_u64_u32 v[66:67], s[12:13], v34, -3, v[64:65]
	v_mad_i64_i32 v[34:35], s[12:13], v104, s33, v[32:33]
	v_lshlrev_b64 v[70:71], 1, v[68:69]
	v_lshl_add_u64 v[34:35], v[34:35], 0, v[70:71]
	s_mov_b32 s0, 0x9a00000
	v_add_co_u32_e32 v34, vcc, s0, v34
	v_or_b32_e32 v103, 1, v104
	s_nop 0
	v_addc_co_u32_e32 v35, vcc, 0, v35, vcc
	global_load_dwordx4 v[92:95], v[34:35], off offset:1536
	v_mad_i64_i32 v[34:35], s[12:13], v103, s33, v[32:33]
	v_lshl_add_u64 v[34:35], v[34:35], 0, v[70:71]
	v_add_co_u32_e32 v34, vcc, s0, v34
	v_or_b32_e32 v101, 2, v104
	s_nop 0
	v_addc_co_u32_e32 v35, vcc, 0, v35, vcc
	global_load_dwordx4 v[44:47], v[34:35], off offset:1536
	v_mad_i64_i32 v[34:35], s[12:13], v101, s33, v[32:33]
	v_lshl_add_u64 v[34:35], v[34:35], 0, v[70:71]
	v_or_b32_e32 v100, 3, v104
	v_add_co_u32_e32 v34, vcc, s0, v34
	v_mad_i64_i32 v[32:33], s[12:13], v100, s33, v[32:33]
	s_nop 0
	v_addc_co_u32_e32 v35, vcc, 0, v35, vcc
	v_lshl_add_u64 v[32:33], v[32:33], 0, v[70:71]
	v_add_co_u32_e32 v32, vcc, s0, v32
	global_load_dwordx4 v[36:39], v[34:35], off offset:1536
	s_nop 0
	v_addc_co_u32_e32 v33, vcc, 0, v33, vcc
	global_load_dwordx4 v[32:35], v[32:33], off offset:1536
	s_waitcnt vmcnt(4)
	v_lshlrev_b32_e32 v76, 16, v50
	v_and_b32_e32 v77, 0xffff0000, v50
	v_lshlrev_b32_e32 v106, 16, v51
	v_and_b32_e32 v83, 0xffff0000, v51
	v_lshlrev_b32_e32 v74, 16, v52
	v_and_b32_e32 v75, 0xffff0000, v52
	v_lshlrev_b32_e32 v72, 16, v53
	v_and_b32_e32 v73, 0xffff0000, v53
	v_lshlrev_b32_e32 v80, 16, v48
	v_and_b32_e32 v81, 0xffff0000, v48
	v_lshlrev_b32_e32 v105, 16, v55
	v_and_b32_e32 v67, 0xffff0000, v55
	v_mov_b32_e32 v55, v11
	v_lshlrev_b32_e32 v78, 16, v49
	v_and_b32_e32 v79, 0xffff0000, v49
	v_lshlrev_b32_e32 v70, 16, v54
	v_and_b32_e32 v71, 0xffff0000, v54
	v_and_b32_e32 v82, 0xffff0000, v43
	v_mov_b32_e32 v84, v3
	v_mov_b32_e32 v85, v7
	v_cmp_gt_i32_e64 s[12:13], 2, v66
	v_cmp_eq_u32_e32 vcc, 0, v66
	v_lshlrev_b32_e32 v66, 16, v43
	v_pk_mul_f32 v[90:91], v[84:85], v[82:83]
	v_mul_f32_e32 v87, v2, v66
	v_mov_b32_e32 v54, v19
	v_mov_b32_e32 v86, v90
	v_mul_f32_e32 v89, v6, v106
	v_mov_b32_e32 v88, v91
	v_mul_f32_e32 v43, v10, v105
	s_waitcnt vmcnt(3)
	v_lshlrev_b32_e32 v52, 16, v92
	v_and_b32_e32 v53, 0xffff0000, v92
	v_lshlrev_b32_e32 v50, 16, v93
	v_and_b32_e32 v51, 0xffff0000, v93
	v_lshlrev_b32_e32 v92, 16, v40
	v_and_b32_e32 v93, 0xffff0000, v40
	v_pk_fma_f32 v[92:93], v[12:13], v[92:93], 0 op_sel_hi:[1,1,0]
	v_lshlrev_b32_e32 v40, 16, v41
	v_pk_fma_f32 v[92:93], v[20:21], v[80:81], v[92:93]
	v_and_b32_e32 v41, 0xffff0000, v41
	v_pk_fma_f32 v[92:93], v[24:25], v[74:75], v[92:93]
	v_pk_fma_f32 v[40:41], v[14:15], v[40:41], 0 op_sel_hi:[1,1,0]
	v_pk_fma_f32 v[92:93], v[28:29], v[52:53], v[92:93]
	v_pk_fma_f32 v[40:41], v[22:23], v[78:79], v[40:41]
	v_mul_f32_e32 v11, 0xbfb8aa3b, v92
	v_exp_f32_e32 v11, v11
	v_pk_fma_f32 v[40:41], v[26:27], v[72:73], v[40:41]
	v_lshlrev_b32_e32 v48, 16, v94
	v_pk_fma_f32 v[40:41], v[30:31], v[50:51], v[40:41]
	v_add_f32_e32 v11, 1.0, v11
	v_rcp_f32_e32 v96, v11
	v_mul_f32_e32 v11, 0xbfb8aa3b, v93
	v_exp_f32_e32 v11, v11
	v_and_b32_e32 v49, 0xffff0000, v94
	v_and_b32_e32 v66, 0xffff0000, v95
	v_lshlrev_b32_e32 v102, 16, v95
	v_add_f32_e32 v11, 1.0, v11
	v_rcp_f32_e32 v97, v11
	v_mul_f32_e32 v11, 0xbfb8aa3b, v40
	v_exp_f32_e32 v11, v11
	v_pk_mul_f32 v[94:95], v[54:55], v[66:67]
	v_pk_mul_f32 v[92:93], v[92:93], v[96:97]
	v_mul_f32_e32 v82, v18, v102
	v_add_f32_e32 v11, 1.0, v11
	v_rcp_f32_e32 v96, v11
	v_mul_f32_e32 v11, 0xbfb8aa3b, v41
	v_exp_f32_e32 v11, v11
	s_nop 0
	v_add_f32_e32 v11, 1.0, v11
	v_rcp_f32_e32 v97, v11
	s_nop 0
	v_pk_mul_f32 v[96:97], v[40:41], v[96:97]
	v_lshlrev_b32_e32 v40, 16, v42
	v_and_b32_e32 v41, 0xffff0000, v42
	v_pk_fma_f32 v[40:41], v[0:1], v[40:41], 0 op_sel_hi:[1,1,0]
	v_mov_b32_e32 v42, v95
	v_pk_fma_f32 v[40:41], v[4:5], v[76:77], v[40:41]
	v_mov_b32_e32 v95, v82
	v_pk_fma_f32 v[40:41], v[8:9], v[70:71], v[40:41]
	s_nop 0
	v_pk_fma_f32 v[40:41], v[16:17], v[48:49], v[40:41]
	s_nop 0
	v_mul_f32_e32 v11, 0xbfb8aa3b, v40
	v_exp_f32_e32 v11, v11
	s_nop 0
	v_add_f32_e32 v11, 1.0, v11
	v_rcp_f32_e32 v98, v11
	v_mul_f32_e32 v11, 0xbfb8aa3b, v41
	v_exp_f32_e32 v11, v11
	s_nop 0
	v_add_f32_e32 v11, 1.0, v11
	v_rcp_f32_e32 v99, v11
	s_nop 0
	v_pk_mul_f32 v[98:99], v[40:41], v[98:99]
	v_pk_add_f32 v[40:41], v[86:87], 0 op_sel_hi:[1,0]
	s_nop 0
	v_pk_add_f32 v[40:41], v[40:41], v[88:89]
	s_nop 0
	v_pk_add_f32 v[40:41], v[40:41], v[42:43]
	s_nop 0
	v_pk_add_f32 v[40:41], v[94:95], v[40:41]
	s_nop 0
	v_mul_f32_e32 v11, 0xbfb8aa3b, v41
	v_exp_f32_e32 v11, v11
	s_nop 0
	v_add_f32_e32 v11, 1.0, v11
	v_rcp_f32_e32 v43, v11
	v_mul_f32_e32 v11, 0xbfb8aa3b, v40
	v_exp_f32_e32 v11, v11
	s_nop 0
	v_add_f32_e32 v11, 1.0, v11
	v_rcp_f32_e32 v42, v11
	s_nop 0
	v_pk_mul_f32 v[42:43], v[40:41], v[42:43]
	s_and_saveexec_b64 s[20:21], s[12:13]
	s_cbranch_execz .LBB0_43
	v_pk_mul_f32 v[40:41], v[92:93], v[92:93]
	v_pk_mul_f32 v[86:87], v[96:97], v[96:97]
	v_add_f32_e32 v11, v40, v41
	v_add_f32_e32 v11, v86, v11
	v_pk_mul_f32 v[88:89], v[98:99], v[98:99]
	v_add_f32_e32 v11, v87, v11
	v_and_b32_e32 v40, 64, v226
	v_add_f32_e32 v11, v88, v11
	v_add_u32_e32 v40, 64, v40
	v_pk_mul_f32 v[90:91], v[42:43], v[42:43]
	v_add_f32_e32 v11, v89, v11
	v_add_f32_e32 v11, v91, v11
	v_add_f32_e32 v11, v90, v11
	s_nop 1
	v_add_f32_dpp v11, v11, v11 quad_perm:[1,0,3,2] row_mask:0xf bank_mask:0xf
	s_nop 1
	s_nop 1
	v_add_f32_dpp v11, v11, v11 quad_perm:[2,3,0,1] row_mask:0xf bank_mask:0xf
	s_nop 1
	s_nop 1
	v_add_f32_dpp v11, v11, v11 row_half_mirror row_mask:0xf bank_mask:0xf
	s_nop 1
	s_nop 1
	v_add_f32_dpp v11, v11, v11 row_mirror row_mask:0xf bank_mask:0xf
	v_add_f32_e32 v11, 0x358637bd, v11
	v_mul_f32_e32 v19, 0x4b800000, v11
	v_cmp_gt_f32_e64 s[14:15], s92, v11
	s_nop 1
	v_cndmask_b32_e64 v11, v11, v19, s[14:15]
	v_rsq_f32_e32 v11, v11
	s_nop 0
	v_mul_f32_e32 v19, 0x45800000, v11
	v_cndmask_b32_e64 v11, v11, v19, s[14:15]
	v_mul_f32_e32 v19, 0x3db504f3, v11
	v_cndmask_b32_e32 v40, v11, v19, vcc
	v_pk_mul_f32 v[92:93], v[92:93], v[40:41] op_sel_hi:[1,0]
	v_pk_mul_f32 v[96:97], v[96:97], v[40:41] op_sel_hi:[1,0]
	v_pk_mul_f32 v[98:99], v[98:99], v[40:41] op_sel_hi:[1,0]
	v_pk_mul_f32 v[42:43], v[42:43], v[40:41] op_sel_hi:[1,0]
; DI unsigned pk_bf16(float a, float b) { bf2_t v = __builtin_convertvector((f2_t){a, b}, bf2_t); return __builtin_bit_cast(unsigned, v); }
; DI float bf_lo(unsigned u) { return __uint_as_float(u << 16); }
; DI float bf_hi(unsigned u) { return __uint_as_float(u & 0xffff0000u); }
; DI float sigmoidf_(float x) { return __builtin_amdgcn_rcpf(1.0f + __expf(-x)); }
; DI void phase_gdn_prep(const Params& P, int l) {
;     ...
;             for (int tk = 0; tk < 4; ++tk) {
;                 float y[8];
; #pragma unroll
;                 for (int e = 0; e < 8; ++e) y[e] = 0.f;
; #pragma unroll
;                 for (int i = 0; i < 4; ++i)
; #pragma unroll
;                     for (int jj = 0; jj < 4; ++jj) {
;                         y[2 * jj] += w[i][jj >> 1][(2 * jj) & 3] * bf_lo(x[tk + i][jj]);
;                         y[2 * jj + 1] += w[i][jj >> 1][(2 * jj + 1) & 3] * bf_hi(x[tk + i][jj]);
;                     }
;                 float ss = 0.f;
; #pragma unroll
;                 for (int e = 0; e < 8; ++e) { y[e] = y[e] * sigmoidf_(y[e]); ss += y[e] * y[e]; }
;                 if (which < 2) {
;                     ss += __shfl_xor(ss, 1); ss += __shfl_xor(ss, 2); ss += __shfl_xor(ss, 4); ss += __shfl_xor(ss, 8);
;                     float sc = rsqrtf(ss + 1e-6f);
;                     if (which == 0) sc *= 0.08838834764831845f;
; #pragma unroll
;                     for (int e = 0; e < 8; ++e) y[e] *= sc;
;                 }
;                 u32x4 o; o.x = pk_bf16(y[0], y[1]); o.y = pk_bf16(y[2], y[3]); o.z = pk_bf16(y[4], y[5]); o.w = pk_bf16(y[6], y[7]);
;                 *(u32x4*)(gq + (size_t)(t0 + tk) * 1536 + c) = o;
.LBB0_43:
	s_or_b64 exec, exec, s[20:21]
	v_readlane_b32 s14, v250, 2
	v_readlane_b32 s15, v250, 3
	v_pk_fma_f32 v[80:81], v[12:13], v[80:81], 0 op_sel_hi:[1,1,0]
	v_cvt_pk_bf16_f32 v86, v92, v93
	v_lshl_add_u64 v[40:41], v[68:69], 1, s[14:15]
	v_cvt_pk_bf16_f32 v87, v96, v97
	v_cvt_pk_bf16_f32 v88, v98, v99
	v_cvt_pk_bf16_f32 v89, v43, v42
	v_mad_i64_i32 v[42:43], s[14:15], v104, s75, v[40:41]
	v_pk_fma_f32 v[80:81], v[20:21], v[74:75], v[80:81]
	global_store_dwordx4 v[42:43], v[86:89], off
	v_mov_b32_e32 v42, v83
	v_mov_b32_e32 v43, v67
	s_waitcnt vmcnt(3)
	v_lshlrev_b32_e32 v68, 16, v44
	v_and_b32_e32 v69, 0xffff0000, v44
	v_pk_fma_f32 v[80:81], v[24:25], v[52:53], v[80:81]
	v_pk_mul_f32 v[82:83], v[84:85], v[42:43]
	v_lshlrev_b32_e32 v42, 16, v46
	v_and_b32_e32 v43, 0xffff0000, v46
	v_lshlrev_b32_e32 v11, 16, v47
	v_and_b32_e32 v46, 0xffff0000, v47
	v_mov_b32_e32 v47, v66
	v_pk_fma_f32 v[80:81], v[28:29], v[68:69], v[80:81]
	v_pk_mul_f32 v[90:91], v[54:55], v[46:47]
	v_mul_f32_e32 v47, 0xbfb8aa3b, v80
	v_exp_f32_e32 v47, v47
	v_pk_fma_f32 v[78:79], v[14:15], v[78:79], 0 op_sel_hi:[1,1,0]
	v_lshlrev_b32_e32 v44, 16, v45
	v_pk_fma_f32 v[78:79], v[22:23], v[72:73], v[78:79]
	v_add_f32_e32 v47, 1.0, v47
	v_rcp_f32_e32 v92, v47
	v_mul_f32_e32 v47, 0xbfb8aa3b, v81
	v_exp_f32_e32 v47, v47
	v_and_b32_e32 v45, 0xffff0000, v45
	v_pk_fma_f32 v[78:79], v[26:27], v[50:51], v[78:79]
	v_mul_f32_e32 v87, v2, v106
	v_add_f32_e32 v47, 1.0, v47
	v_pk_fma_f32 v[78:79], v[30:31], v[44:45], v[78:79]
	v_rcp_f32_e32 v93, v47
	v_mul_f32_e32 v47, 0xbfb8aa3b, v78
	v_exp_f32_e32 v47, v47
	v_mov_b32_e32 v86, v82
	v_pk_mul_f32 v[80:81], v[80:81], v[92:93]
	v_mul_f32_e32 v89, v6, v105
	v_add_f32_e32 v47, 1.0, v47
	v_rcp_f32_e32 v92, v47
	v_mul_f32_e32 v47, 0xbfb8aa3b, v79
	v_exp_f32_e32 v47, v47
	v_pk_fma_f32 v[76:77], v[0:1], v[76:77], 0 op_sel_hi:[1,1,0]
	v_pk_add_f32 v[86:87], v[86:87], 0 op_sel_hi:[1,0]
	v_mov_b32_e32 v88, v83
	v_mul_f32_e32 v85, v10, v102
	v_mul_f32_e32 v19, v18, v11
	v_pk_fma_f32 v[76:77], v[4:5], v[70:71], v[76:77]
	v_pk_add_f32 v[82:83], v[86:87], v[88:89]
	v_mov_b32_e32 v84, v91
	v_pk_fma_f32 v[76:77], v[8:9], v[48:49], v[76:77]
	v_pk_add_f32 v[82:83], v[84:85], v[82:83]
	v_mov_b32_e32 v91, v19
	v_add_f32_e32 v47, 1.0, v47
	v_pk_fma_f32 v[76:77], v[16:17], v[42:43], v[76:77]
	v_pk_add_f32 v[82:83], v[90:91], v[82:83]
	v_rcp_f32_e32 v93, v47
	v_mul_f32_e32 v47, 0xbfb8aa3b, v76
	v_mul_f32_e32 v19, 0xbfb8aa3b, v83
	v_exp_f32_e32 v47, v47
	v_exp_f32_e32 v19, v19
	v_pk_mul_f32 v[78:79], v[78:79], v[92:93]
	v_add_f32_e32 v47, 1.0, v47
	v_add_f32_e32 v19, 1.0, v19
	v_rcp_f32_e32 v92, v47
	v_mul_f32_e32 v47, 0xbfb8aa3b, v77
	v_rcp_f32_e32 v85, v19
	v_mul_f32_e32 v19, 0xbfb8aa3b, v82
	v_exp_f32_e32 v47, v47
	v_exp_f32_e32 v19, v19
	v_add_f32_e32 v47, 1.0, v47
	v_add_f32_e32 v19, 1.0, v19
	v_rcp_f32_e32 v93, v47
	v_rcp_f32_e32 v84, v19
	v_pk_mul_f32 v[76:77], v[76:77], v[92:93]
	v_pk_mul_f32 v[82:83], v[82:83], v[84:85]
	s_and_saveexec_b64 s[20:21], s[12:13]
	s_cbranch_execz .LBB0_45
	v_pk_mul_f32 v[84:85], v[80:81], v[80:81]
	v_pk_mul_f32 v[86:87], v[78:79], v[78:79]
	v_add_f32_e32 v19, v84, v85
	v_add_f32_e32 v19, v86, v19
	v_pk_mul_f32 v[88:89], v[76:77], v[76:77]
	v_add_f32_e32 v19, v87, v19
	v_and_b32_e32 v84, 64, v226
	v_add_f32_e32 v19, v88, v19
	v_add_u32_e32 v84, 64, v84
	v_pk_mul_f32 v[90:91], v[82:83], v[82:83]
	v_add_f32_e32 v19, v89, v19
	v_cmp_lt_i32_e64 s[14:15], v47, v84
	v_add_f32_e32 v19, v91, v19
	v_add_f32_e32 v19, v90, v19
	s_nop 1
	v_add_f32_dpp v19, v19, v19 quad_perm:[1,0,3,2] row_mask:0xf bank_mask:0xf
	v_cmp_lt_i32_e64 s[14:15], v47, v84
	s_nop 1
	s_nop 1
	v_add_f32_dpp v19, v19, v19 quad_perm:[2,3,0,1] row_mask:0xf bank_mask:0xf
	v_cmp_lt_i32_e64 s[14:15], v47, v84
	s_nop 1
	s_nop 1
	v_add_f32_dpp v19, v19, v19 row_half_mirror row_mask:0xf bank_mask:0xf
	v_cmp_lt_i32_e64 s[14:15], v47, v84
	s_nop 1
	s_nop 1
	v_add_f32_dpp v19, v19, v19 row_mirror row_mask:0xf bank_mask:0xf
	v_add_f32_e32 v19, 0x358637bd, v19
	v_mul_f32_e32 v47, 0x4b800000, v19
	v_cmp_gt_f32_e64 s[14:15], s92, v19
	s_nop 1
	v_cndmask_b32_e64 v19, v19, v47, s[14:15]
	v_rsq_f32_e32 v19, v19
	s_nop 0
	v_mul_f32_e32 v47, 0x45800000, v19
	v_cndmask_b32_e64 v19, v19, v47, s[14:15]
	v_mul_f32_e32 v47, 0x3db504f3, v19
	v_cndmask_b32_e32 v84, v19, v47, vcc
	v_pk_mul_f32 v[80:81], v[80:81], v[84:85] op_sel_hi:[1,0]
	v_pk_mul_f32 v[78:79], v[78:79], v[84:85] op_sel_hi:[1,0]
	v_pk_mul_f32 v[76:77], v[76:77], v[84:85] op_sel_hi:[1,0]
	v_pk_mul_f32 v[82:83], v[82:83], v[84:85] op_sel_hi:[1,0]
; DI unsigned pk_bf16(float a, float b) { bf2_t v = __builtin_convertvector((f2_t){a, b}, bf2_t); return __builtin_bit_cast(unsigned, v); }
; DI float bf_lo(unsigned u) { return __uint_as_float(u << 16); }
; DI float bf_hi(unsigned u) { return __uint_as_float(u & 0xffff0000u); }
; DI float sigmoidf_(float x) { return __builtin_amdgcn_rcpf(1.0f + __expf(-x)); }
; DI void phase_gdn_prep(const Params& P, int l) {
;     ...
;             for (int tk = 0; tk < 4; ++tk) {
;                 float y[8];
; #pragma unroll
;                 for (int e = 0; e < 8; ++e) y[e] = 0.f;
; #pragma unroll
;                 for (int i = 0; i < 4; ++i)
; #pragma unroll
;                     for (int jj = 0; jj < 4; ++jj) {
;                         y[2 * jj] += w[i][jj >> 1][(2 * jj) & 3] * bf_lo(x[tk + i][jj]);
;                         y[2 * jj + 1] += w[i][jj >> 1][(2 * jj + 1) & 3] * bf_hi(x[tk + i][jj]);
;                     }
;                 float ss = 0.f;
; #pragma unroll
;                 for (int e = 0; e < 8; ++e) { y[e] = y[e] * sigmoidf_(y[e]); ss += y[e] * y[e]; }
;                 if (which < 2) {
;                     ss += __shfl_xor(ss, 1); ss += __shfl_xor(ss, 2); ss += __shfl_xor(ss, 4); ss += __shfl_xor(ss, 8);
;                     float sc = rsqrtf(ss + 1e-6f);
;                     if (which == 0) sc *= 0.08838834764831845f;
; #pragma unroll
;                     for (int e = 0; e < 8; ++e) y[e] *= sc;
;                 }
;                 u32x4 o; o.x = pk_bf16(y[0], y[1]); o.y = pk_bf16(y[2], y[3]); o.z = pk_bf16(y[4], y[5]); o.w = pk_bf16(y[6], y[7]);
;                 *(u32x4*)(gq + (size_t)(t0 + tk) * 1536 + c) = o;
.LBB0_45:
	s_or_b64 exec, exec, s[20:21]
	v_pk_fma_f32 v[74:75], v[12:13], v[74:75], 0 op_sel_hi:[1,1,0]
	v_cvt_pk_bf16_f32 v84, v80, v81
	v_pk_fma_f32 v[74:75], v[20:21], v[52:53], v[74:75]
	v_cvt_pk_bf16_f32 v85, v78, v79
	v_cvt_pk_bf16_f32 v86, v76, v77
	v_cvt_pk_bf16_f32 v87, v83, v82
	v_mad_i64_i32 v[76:77], s[14:15], v103, s75, v[40:41]
	s_waitcnt vmcnt(2)
	v_lshlrev_b32_e32 v78, 16, v36
	v_and_b32_e32 v79, 0xffff0000, v36
	v_pk_fma_f32 v[74:75], v[24:25], v[68:69], v[74:75]
	global_store_dwordx4 v[76:77], v[84:87], off
	v_mov_b32_e32 v81, v3
	v_lshlrev_b32_e32 v76, 16, v37
	v_and_b32_e32 v77, 0xffff0000, v37
	v_lshlrev_b32_e32 v36, 16, v38
	v_and_b32_e32 v37, 0xffff0000, v38
	v_lshlrev_b32_e32 v3, 16, v39
	v_and_b32_e32 v38, 0xffff0000, v39
	v_mov_b32_e32 v39, v46
	v_pk_fma_f32 v[74:75], v[28:29], v[78:79], v[74:75]
	v_pk_mul_f32 v[88:89], v[54:55], v[38:39]
	v_mul_f32_e32 v39, 0xbfb8aa3b, v74
	v_exp_f32_e32 v39, v39
	v_pk_fma_f32 v[72:73], v[14:15], v[72:73], 0 op_sel_hi:[1,1,0]
	v_mov_b32_e32 v80, v7
	v_pk_fma_f32 v[72:73], v[22:23], v[50:51], v[72:73]
	v_add_f32_e32 v39, 1.0, v39
	v_rcp_f32_e32 v90, v39
	v_mul_f32_e32 v39, 0xbfb8aa3b, v75
	v_exp_f32_e32 v39, v39
	v_pk_fma_f32 v[72:73], v[26:27], v[44:45], v[72:73]
	v_pk_mul_f32 v[84:85], v[80:81], v[66:67]
	v_pk_fma_f32 v[72:73], v[30:31], v[76:77], v[72:73]
	v_add_f32_e32 v39, 1.0, v39
	v_rcp_f32_e32 v91, v39
	v_mul_f32_e32 v39, 0xbfb8aa3b, v72
	v_exp_f32_e32 v39, v39
	v_mul_f32_e32 v83, v2, v105
	v_pk_mul_f32 v[74:75], v[74:75], v[90:91]
	v_mul_f32_e32 v7, v6, v102
	v_add_f32_e32 v39, 1.0, v39
	v_rcp_f32_e32 v90, v39
	v_mul_f32_e32 v39, 0xbfb8aa3b, v73
	v_exp_f32_e32 v39, v39
	v_mov_b32_e32 v82, v85
	v_pk_fma_f32 v[70:71], v[0:1], v[70:71], 0 op_sel_hi:[1,1,0]
	v_pk_add_f32 v[82:83], v[82:83], 0 op_sel_hi:[1,0]
	v_mov_b32_e32 v85, v7
	v_mul_f32_e32 v87, v10, v11
	v_mul_f32_e32 v19, v18, v3
	v_pk_fma_f32 v[70:71], v[4:5], v[48:49], v[70:71]
	v_pk_add_f32 v[82:83], v[84:85], v[82:83]
	v_mov_b32_e32 v86, v89
	v_pk_fma_f32 v[70:71], v[8:9], v[42:43], v[70:71]
	v_pk_add_f32 v[82:83], v[86:87], v[82:83]
	v_mov_b32_e32 v89, v19
	v_add_f32_e32 v39, 1.0, v39
	v_pk_fma_f32 v[70:71], v[16:17], v[36:37], v[70:71]
	v_pk_add_f32 v[82:83], v[88:89], v[82:83]
	v_rcp_f32_e32 v91, v39
	v_mul_f32_e32 v39, 0xbfb8aa3b, v70
	v_mul_f32_e32 v7, 0xbfb8aa3b, v83
	v_exp_f32_e32 v39, v39
	v_exp_f32_e32 v7, v7
	v_pk_mul_f32 v[72:73], v[72:73], v[90:91]
	v_add_f32_e32 v39, 1.0, v39
	v_add_f32_e32 v7, 1.0, v7
	v_rcp_f32_e32 v90, v39
	v_mul_f32_e32 v39, 0xbfb8aa3b, v71
	v_rcp_f32_e32 v85, v7
	v_mul_f32_e32 v7, 0xbfb8aa3b, v82
	v_exp_f32_e32 v39, v39
	v_exp_f32_e32 v7, v7
	v_add_f32_e32 v39, 1.0, v39
	v_add_f32_e32 v7, 1.0, v7
	v_rcp_f32_e32 v91, v39
	v_rcp_f32_e32 v84, v7
	v_pk_mul_f32 v[70:71], v[70:71], v[90:91]
	v_pk_mul_f32 v[82:83], v[82:83], v[84:85]
	s_and_saveexec_b64 s[20:21], s[12:13]
	s_cbranch_execz .LBB0_47
	v_pk_mul_f32 v[84:85], v[74:75], v[74:75]
	v_pk_mul_f32 v[86:87], v[72:73], v[72:73]
	v_add_f32_e32 v7, v84, v85
	v_add_f32_e32 v7, v86, v7
	v_pk_mul_f32 v[88:89], v[70:71], v[70:71]
	v_add_f32_e32 v7, v87, v7
	v_and_b32_e32 v39, 64, v226
	v_add_f32_e32 v7, v88, v7
	v_add_u32_e32 v39, 64, v39
	v_pk_mul_f32 v[90:91], v[82:83], v[82:83]
	v_add_f32_e32 v7, v89, v7
	v_cmp_lt_i32_e64 s[14:15], v19, v39
	v_add_f32_e32 v7, v91, v7
	v_add_f32_e32 v7, v90, v7
	s_nop 1
	v_add_f32_dpp v7, v7, v7 quad_perm:[1,0,3,2] row_mask:0xf bank_mask:0xf
	v_cmp_lt_i32_e64 s[14:15], v19, v39
	s_nop 1
	s_nop 1
	v_add_f32_dpp v7, v7, v7 quad_perm:[2,3,0,1] row_mask:0xf bank_mask:0xf
	v_cmp_lt_i32_e64 s[14:15], v19, v39
	s_nop 1
	s_nop 1
	v_add_f32_dpp v7, v7, v7 row_half_mirror row_mask:0xf bank_mask:0xf
	v_cmp_lt_i32_e64 s[14:15], v19, v39
	s_nop 1
	s_nop 1
	v_add_f32_dpp v7, v7, v7 row_mirror row_mask:0xf bank_mask:0xf
	v_add_f32_e32 v7, 0x358637bd, v7
	v_mul_f32_e32 v19, 0x4b800000, v7
	v_cmp_gt_f32_e64 s[14:15], s92, v7
	s_nop 1
	v_cndmask_b32_e64 v7, v7, v19, s[14:15]
	v_rsq_f32_e32 v7, v7
	s_nop 0
	v_mul_f32_e32 v19, 0x45800000, v7
	v_cndmask_b32_e64 v7, v7, v19, s[14:15]
	v_mul_f32_e32 v19, 0x3db504f3, v7
	v_cndmask_b32_e32 v84, v7, v19, vcc
	v_pk_mul_f32 v[74:75], v[74:75], v[84:85] op_sel_hi:[1,0]
	v_pk_mul_f32 v[72:73], v[72:73], v[84:85] op_sel_hi:[1,0]
	v_pk_mul_f32 v[70:71], v[70:71], v[84:85] op_sel_hi:[1,0]
	v_pk_mul_f32 v[82:83], v[82:83], v[84:85] op_sel_hi:[1,0]
; DI unsigned pk_bf16(float a, float b) { bf2_t v = __builtin_convertvector((f2_t){a, b}, bf2_t); return __builtin_bit_cast(unsigned, v); }
; DI float bf_lo(unsigned u) { return __uint_as_float(u << 16); }
; DI float bf_hi(unsigned u) { return __uint_as_float(u & 0xffff0000u); }
; DI float sigmoidf_(float x) { return __builtin_amdgcn_rcpf(1.0f + __expf(-x)); }
; DI void phase_gdn_prep(const Params& P, int l) {
;     ...
;             for (int tk = 0; tk < 4; ++tk) {
;                 float y[8];
; #pragma unroll
;                 for (int e = 0; e < 8; ++e) y[e] = 0.f;
; #pragma unroll
;                 for (int i = 0; i < 4; ++i)
; #pragma unroll
;                     for (int jj = 0; jj < 4; ++jj) {
;                         y[2 * jj] += w[i][jj >> 1][(2 * jj) & 3] * bf_lo(x[tk + i][jj]);
;                         y[2 * jj + 1] += w[i][jj >> 1][(2 * jj + 1) & 3] * bf_hi(x[tk + i][jj]);
;                     }
;                 float ss = 0.f;
; #pragma unroll
;                 for (int e = 0; e < 8; ++e) { y[e] = y[e] * sigmoidf_(y[e]); ss += y[e] * y[e]; }
;                 if (which < 2) {
;                     ss += __shfl_xor(ss, 1); ss += __shfl_xor(ss, 2); ss += __shfl_xor(ss, 4); ss += __shfl_xor(ss, 8);
;                     float sc = rsqrtf(ss + 1e-6f);
;                     if (which == 0) sc *= 0.08838834764831845f;
; #pragma unroll
;                     for (int e = 0; e < 8; ++e) y[e] *= sc;
;                 }
;                 u32x4 o; o.x = pk_bf16(y[0], y[1]); o.y = pk_bf16(y[2], y[3]); o.z = pk_bf16(y[4], y[5]); o.w = pk_bf16(y[6], y[7]);
;                 *(u32x4*)(gq + (size_t)(t0 + tk) * 1536 + c) = o;
.LBB0_47:
	s_or_b64 exec, exec, s[20:21]
	v_pk_fma_f32 v[12:13], v[12:13], v[52:53], 0 op_sel_hi:[1,1,0]
	v_mul_f32_e32 v7, v2, v102
	v_mul_f32_e32 v2, v6, v11
	s_waitcnt vmcnt(2)
	v_lshlrev_b32_e32 v6, 16, v35
	v_pk_fma_f32 v[12:13], v[20:21], v[68:69], v[12:13]
	v_mul_f32_e32 v39, v18, v6
	v_pk_fma_f32 v[12:13], v[24:25], v[78:79], v[12:13]
	v_lshlrev_b32_e32 v18, 16, v32
	v_and_b32_e32 v19, 0xffff0000, v32
	v_pk_fma_f32 v[12:13], v[28:29], v[18:19], v[12:13]
	v_pk_fma_f32 v[14:15], v[14:15], v[50:51], 0 op_sel_hi:[1,1,0]
	v_mul_f32_e32 v6, 0xbfb8aa3b, v12
	v_exp_f32_e32 v6, v6
	v_mul_f32_e32 v18, 0xbfb8aa3b, v13
	v_exp_f32_e32 v19, v18
	v_pk_fma_f32 v[14:15], v[22:23], v[44:45], v[14:15]
	v_lshlrev_b32_e32 v20, 16, v33
	v_pk_fma_f32 v[14:15], v[26:27], v[76:77], v[14:15]
	v_and_b32_e32 v21, 0xffff0000, v33
	v_pk_fma_f32 v[0:1], v[0:1], v[48:49], 0 op_sel_hi:[1,1,0]
	v_add_f32_e32 v6, 1.0, v6
	v_pk_fma_f32 v[14:15], v[30:31], v[20:21], v[14:15]
	v_pk_fma_f32 v[0:1], v[4:5], v[42:43], v[0:1]
	v_rcp_f32_e32 v18, v6
	v_add_f32_e32 v6, 1.0, v19
	v_mul_f32_e32 v19, 0xbfb8aa3b, v14
	v_pk_fma_f32 v[0:1], v[8:9], v[36:37], v[0:1]
	v_lshlrev_b32_e32 v4, 16, v34
	v_and_b32_e32 v5, 0xffff0000, v34
	v_exp_f32_e32 v20, v19
	v_mul_f32_e32 v19, 0xbfb8aa3b, v15
	v_pk_fma_f32 v[4:5], v[16:17], v[4:5], v[0:1]
	v_exp_f32_e32 v21, v19
	v_mul_f32_e32 v0, 0xbfb8aa3b, v4
	v_exp_f32_e32 v0, v0
	v_mul_f32_e32 v1, 0xbfb8aa3b, v5
	v_exp_f32_e32 v1, v1
	v_mov_b32_e32 v47, v66
	v_rcp_f32_e32 v19, v6
	v_add_f32_e32 v6, 1.0, v20
	v_pk_mul_f32 v[46:47], v[80:81], v[46:47]
	v_rcp_f32_e32 v20, v6
	v_add_f32_e32 v6, 1.0, v21
	v_mul_f32_e32 v3, v10, v3
	v_and_b32_e32 v10, 0xffff0000, v35
	v_mov_b32_e32 v11, v38
	v_rcp_f32_e32 v21, v6
	v_add_f32_e32 v0, 1.0, v0
	v_mov_b32_e32 v6, v47
	v_pk_mul_f32 v[10:11], v[54:55], v[10:11]
	v_rcp_f32_e32 v8, v0
	v_add_f32_e32 v9, 1.0, v1
	v_pk_add_f32 v[0:1], v[6:7], 0 op_sel_hi:[1,0]
	v_mov_b32_e32 v47, v2
	v_pk_add_f32 v[0:1], v[46:47], v[0:1]
	v_mov_b32_e32 v2, v11
	v_pk_add_f32 v[0:1], v[2:3], v[0:1]
	v_mov_b32_e32 v11, v39
	v_pk_add_f32 v[6:7], v[10:11], v[0:1]
	v_rcp_f32_e32 v9, v9
	v_mul_f32_e32 v0, 0xbfb8aa3b, v7
	v_exp_f32_e32 v0, v0
	v_mul_f32_e32 v1, 0xbfb8aa3b, v6
	v_exp_f32_e32 v1, v1
	v_cvt_pk_bf16_f32 v84, v74, v75
	v_add_f32_e32 v0, 1.0, v0
	v_rcp_f32_e32 v11, v0
	v_add_f32_e32 v0, 1.0, v1
	v_rcp_f32_e32 v10, v0
	v_cvt_pk_bf16_f32 v85, v72, v73
	v_cvt_pk_bf16_f32 v86, v70, v71
	v_cvt_pk_bf16_f32 v87, v83, v82
	v_mad_i64_i32 v[70:71], s[14:15], v101, s75, v[40:41]
	v_pk_mul_f32 v[0:1], v[12:13], v[18:19]
	v_pk_mul_f32 v[2:3], v[14:15], v[20:21]
	v_pk_mul_f32 v[4:5], v[4:5], v[8:9]
	v_pk_mul_f32 v[6:7], v[6:7], v[10:11]
	global_store_dwordx4 v[70:71], v[84:87], off
	s_and_saveexec_b64 s[14:15], s[12:13]
	s_cbranch_execz .LBB0_22
	v_pk_mul_f32 v[8:9], v[0:1], v[0:1]
	v_pk_mul_f32 v[10:11], v[2:3], v[2:3]
	v_add_f32_e32 v8, v8, v9
	v_add_f32_e32 v8, v10, v8
	v_pk_mul_f32 v[12:13], v[4:5], v[4:5]
	v_add_f32_e32 v8, v11, v8
	v_and_b32_e32 v10, 64, v226
	v_add_f32_e32 v8, v12, v8
	v_add_u32_e32 v10, 64, v10
	v_pk_mul_f32 v[14:15], v[6:7], v[6:7]
	v_add_f32_e32 v8, v13, v8
	v_cmp_lt_i32_e64 s[12:13], v9, v10
	v_add_f32_e32 v8, v15, v8
	v_add_f32_e32 v8, v14, v8
	v_cndmask_b32_e64 v9, v226, v9, s[12:13]
	s_nop 1
	v_add_f32_dpp v8, v8, v8 quad_perm:[1,0,3,2] row_mask:0xf bank_mask:0xf
	v_cmp_lt_i32_e64 s[12:13], v9, v10
	s_nop 1
	v_cndmask_b32_e64 v9, v226, v9, s[12:13]
	s_nop 1
	v_add_f32_dpp v8, v8, v8 quad_perm:[2,3,0,1] row_mask:0xf bank_mask:0xf
	v_cmp_lt_i32_e64 s[12:13], v9, v10
	s_nop 1
	v_cndmask_b32_e64 v9, v226, v9, s[12:13]
	s_nop 1
	v_add_f32_dpp v8, v8, v8 row_half_mirror row_mask:0xf bank_mask:0xf
	v_cmp_lt_i32_e64 s[12:13], v9, v10
	s_nop 1
	v_cndmask_b32_e64 v9, v226, v9, s[12:13]
	s_nop 1
	v_add_f32_dpp v8, v8, v8 row_mirror row_mask:0xf bank_mask:0xf
	v_add_f32_e32 v8, 0x358637bd, v8
	v_mul_f32_e32 v9, 0x4b800000, v8
	v_cmp_gt_f32_e64 s[12:13], s92, v8
	s_nop 1
	v_cndmask_b32_e64 v8, v8, v9, s[12:13]
	v_rsq_f32_e32 v8, v8
	s_nop 0
	v_mul_f32_e32 v9, 0x45800000, v8
	v_cndmask_b32_e64 v8, v8, v9, s[12:13]
	v_mul_f32_e32 v9, 0x3db504f3, v8
	v_cndmask_b32_e32 v8, v8, v9, vcc
	v_pk_mul_f32 v[0:1], v[0:1], v[8:9] op_sel_hi:[1,0]
	v_pk_mul_f32 v[2:3], v[2:3], v[8:9] op_sel_hi:[1,0]
	v_pk_mul_f32 v[4:5], v[4:5], v[8:9] op_sel_hi:[1,0]
	v_pk_mul_f32 v[6:7], v[6:7], v[8:9] op_sel_hi:[1,0]
	s_branch .LBB0_22
